# SGU LayerNorm: the 5-level sum/sum-of-squares butterflies use DPP row permutes and v_permlane16_swap instead of 10 ds_bpermute round trips per row (same pairing and operand values)
# baseline (speedup 1.0000x reference)
.LBB0_684:
	v_add_u32_e32 v2, 0xffffff90, v0
	v_mad_i64_i32 v[184:185], s[0:1], v2, s9, v[168:169]
	v_add_u32_e32 v2, 0xffffffa0, v0
	v_mad_i64_i32 v[182:183], s[0:1], v2, s9, v[168:169]
	v_add_u32_e32 v2, 0xffffffb0, v0
	v_mad_i64_i32 v[180:181], s[0:1], v2, s9, v[168:169]
	v_subrev_u32_e32 v2, 64, v0
	v_mad_i64_i32 v[178:179], s[0:1], v2, s9, v[168:169]
	v_subrev_u32_e32 v2, 48, v0
	v_mad_i64_i32 v[176:177], s[0:1], v2, s9, v[168:169]
	v_subrev_u32_e32 v2, 32, v0
	v_mad_i64_i32 v[174:175], s[0:1], v2, s9, v[168:169]
	v_add_u32_e32 v2, -16, v0
	v_mad_i64_i32 v[172:173], s[0:1], v2, s9, v[168:169]
	global_load_dwordx4 v[34:37], v[184:185], off offset:2560
	global_load_dwordx4 v[38:41], v[182:183], off offset:2560
	global_load_dwordx4 v[30:33], v[180:181], off offset:2560
	global_load_dwordx4 v[26:29], v[178:179], off offset:2560
	global_load_dwordx4 v[22:25], v[176:177], off offset:2560
	global_load_dwordx4 v[18:21], v[174:175], off offset:2560
	v_mad_i64_i32 v[170:171], s[0:1], v0, s9, v[168:169]
	global_load_dwordx4 v[14:17], v[172:173], off offset:2560
	global_load_dwordx4 v[10:13], v[170:171], off offset:2560
	global_load_dwordx4 v[2:5], v[154:155], off offset:16
	global_load_dwordx4 v[6:9], v[154:155], off
	s_waitcnt vmcnt(9)
	v_lshlrev_b32_e32 v50, 16, v34
	v_and_b32_e32 v51, 0xffff0000, v34
	v_add_f32_e32 v52, 0, v50
	v_lshlrev_b32_e32 v46, 16, v35
	v_add_f32_e32 v52, v52, v51
	v_add_f32_e32 v53, v52, v46
	v_mul_f32_e32 v52, v50, v50
	v_and_b32_e32 v47, 0xffff0000, v35
	v_mov_b32_e32 v34, v46
	v_mov_b32_e32 v35, v50
	v_fmac_f32_e32 v52, v51, v51
	v_lshlrev_b32_e32 v44, 16, v36
	v_pk_fma_f32 v[34:35], v[34:35], v[34:35], v[52:53] op_sel_hi:[1,1,0]
	v_add_f32_e32 v53, v53, v47
	v_mul_f32_e32 v52, v47, v47
	v_and_b32_e32 v45, 0xffff0000, v36
	v_mov_b32_e32 v48, v44
	v_mov_b32_e32 v49, v47
	v_pk_add_f32 v[34:35], v[52:53], v[34:35] op_sel_hi:[0,1]
	v_add_f32_e32 v52, v53, v44
	v_lshlrev_b32_e32 v42, 16, v37
	v_pk_fma_f32 v[34:35], v[48:49], v[48:49], v[34:35]
	v_add_f32_e32 v49, v52, v45
	v_mul_f32_e32 v48, v45, v45
	v_and_b32_e32 v43, 0xffff0000, v37
	v_mov_b32_e32 v36, v42
	v_mov_b32_e32 v37, v45
	v_pk_add_f32 v[34:35], v[48:49], v[34:35] op_sel_hi:[0,1]
	v_pk_fma_f32 v[34:35], v[36:37], v[36:37], v[34:35]
	v_add_f32_e32 v49, v49, v42
	v_mul_f32_e32 v48, v43, v43
	v_mov_b32_e32 v35, v43
	v_pk_add_f32 v[34:35], v[48:49], v[34:35]
	s_nop 1
	v_add_f32_dpp v34, v34, v34 quad_perm:[1,0,3,2] row_mask:0xf bank_mask:0xf
	v_add_f32_dpp v35, v35, v35 quad_perm:[1,0,3,2] row_mask:0xf bank_mask:0xf
	s_nop 0
	v_add_f32_dpp v34, v34, v34 quad_perm:[2,3,0,1] row_mask:0xf bank_mask:0xf
	v_add_f32_dpp v35, v35, v35 quad_perm:[2,3,0,1] row_mask:0xf bank_mask:0xf
	s_nop 0
	v_add_f32_dpp v34, v34, v34 row_half_mirror row_mask:0xf bank_mask:0xf
	v_add_f32_dpp v35, v35, v35 row_half_mirror row_mask:0xf bank_mask:0xf
	s_nop 0
	v_add_f32_dpp v34, v34, v34 row_mirror row_mask:0xf bank_mask:0xf
	v_add_f32_dpp v35, v35, v35 row_mirror row_mask:0xf bank_mask:0xf
	s_nop 0
	v_mov_b32_e32 v36, v34
	v_mov_b32_e32 v37, v35
	s_nop 1
	v_permlane16_swap_b32_e32 v34, v36
	v_permlane16_swap_b32_e32 v35, v37
	s_nop 0
	v_pk_add_f32 v[34:35], v[34:35], v[36:37]
	s_nop 0
	v_pk_mul_f32 v[48:49], v[34:35], s[6:7] op_sel_hi:[1,0]
	s_nop 0
	v_fma_f32 v34, -v49, v49, v48
	v_max_f32_e32 v34, 0, v34
	v_add_f32_e32 v34, 0x3727c5ac, v34
	v_rsq_f32_e32 v52, v34
	v_pk_add_f32 v[34:35], v[50:51], v[48:49] op_sel:[0,1] neg_lo:[0,1] neg_hi:[0,1]
	v_pk_add_f32 v[36:37], v[46:47], v[48:49] op_sel:[0,1] neg_lo:[0,1] neg_hi:[0,1]
	v_pk_add_f32 v[42:43], v[42:43], v[48:49] op_sel:[0,1] neg_lo:[0,1] neg_hi:[0,1]
	v_pk_mul_f32 v[34:35], v[34:35], v[52:53] op_sel_hi:[1,0]
	v_pk_mul_f32 v[36:37], v[36:37], v[52:53] op_sel_hi:[1,0]
	s_waitcnt vmcnt(0)
	v_pk_mul_f32 v[34:35], v[6:7], v[34:35]
	v_pk_mul_f32 v[36:37], v[8:9], v[36:37]
	v_cvt_pk_bf16_f32 v34, v34, v35
	v_cvt_pk_bf16_f32 v35, v36, v37
	v_pk_add_f32 v[36:37], v[44:45], v[48:49] op_sel:[0,1] neg_lo:[0,1] neg_hi:[0,1]
	v_pk_mul_f32 v[42:43], v[42:43], v[52:53] op_sel_hi:[1,0]
	v_pk_mul_f32 v[36:37], v[36:37], v[52:53] op_sel_hi:[1,0]
	v_pk_mul_f32 v[42:43], v[4:5], v[42:43]
	v_pk_mul_f32 v[36:37], v[2:3], v[36:37]
	v_lshlrev_b32_e32 v46, 16, v38
	v_cvt_pk_bf16_f32 v36, v36, v37
	v_cvt_pk_bf16_f32 v37, v42, v43
	v_and_b32_e32 v47, 0xffff0000, v38
	v_add_f32_e32 v48, 0, v46
	ds_write_b128 v205, v[34:37]
	v_lshlrev_b32_e32 v36, 16, v40
	v_and_b32_e32 v37, 0xffff0000, v40
	v_lshlrev_b32_e32 v40, 16, v39
	v_add_f32_e32 v48, v48, v47
	v_add_f32_e32 v49, v48, v40
	v_mul_f32_e32 v48, v46, v46
	v_lshlrev_b32_e32 v42, 16, v41
	v_and_b32_e32 v43, 0xffff0000, v41
	v_and_b32_e32 v41, 0xffff0000, v39
	v_mov_b32_e32 v38, v40
	v_mov_b32_e32 v39, v46
	v_fmac_f32_e32 v48, v47, v47
	v_pk_fma_f32 v[38:39], v[38:39], v[38:39], v[48:49] op_sel_hi:[1,1,0]
	v_add_f32_e32 v49, v49, v41
	v_mul_f32_e32 v48, v41, v41
	v_mov_b32_e32 v44, v36
	v_mov_b32_e32 v45, v41
	v_pk_add_f32 v[38:39], v[48:49], v[38:39] op_sel_hi:[0,1]
	v_add_f32_e32 v48, v49, v36
	v_pk_fma_f32 v[38:39], v[44:45], v[44:45], v[38:39]
	v_add_f32_e32 v45, v48, v37
	v_mul_f32_e32 v44, v37, v37
	v_mov_b32_e32 v34, v42
	v_mov_b32_e32 v35, v37
	v_pk_add_f32 v[38:39], v[44:45], v[38:39] op_sel_hi:[0,1]
	v_pk_fma_f32 v[34:35], v[34:35], v[34:35], v[38:39]
	v_add_f32_e32 v45, v45, v42
	v_mul_f32_e32 v44, v43, v43
	v_mov_b32_e32 v35, v43
	v_pk_add_f32 v[34:35], v[44:45], v[34:35]
	s_nop 1
	v_add_f32_dpp v34, v34, v34 quad_perm:[1,0,3,2] row_mask:0xf bank_mask:0xf
	v_add_f32_dpp v35, v35, v35 quad_perm:[1,0,3,2] row_mask:0xf bank_mask:0xf
	s_nop 0
	v_add_f32_dpp v34, v34, v34 quad_perm:[2,3,0,1] row_mask:0xf bank_mask:0xf
	v_add_f32_dpp v35, v35, v35 quad_perm:[2,3,0,1] row_mask:0xf bank_mask:0xf
	s_nop 0
	v_add_f32_dpp v34, v34, v34 row_half_mirror row_mask:0xf bank_mask:0xf
	v_add_f32_dpp v35, v35, v35 row_half_mirror row_mask:0xf bank_mask:0xf
	s_nop 0
	v_add_f32_dpp v34, v34, v34 row_mirror row_mask:0xf bank_mask:0xf
	v_add_f32_dpp v35, v35, v35 row_mirror row_mask:0xf bank_mask:0xf
	s_nop 0
	v_mov_b32_e32 v38, v34
	v_mov_b32_e32 v39, v35
	s_nop 1
	v_permlane16_swap_b32_e32 v34, v38
	v_permlane16_swap_b32_e32 v35, v39
	s_nop 0
	v_pk_add_f32 v[34:35], v[34:35], v[38:39]
	s_nop 0
	v_pk_mul_f32 v[38:39], v[34:35], s[6:7] op_sel_hi:[1,0]
	s_nop 0
	v_fma_f32 v34, -v39, v39, v38
	v_max_f32_e32 v34, 0, v34
	v_add_f32_e32 v34, 0x3727c5ac, v34
	v_rsq_f32_e32 v44, v34
	v_pk_add_f32 v[34:35], v[46:47], v[38:39] op_sel:[0,1] neg_lo:[0,1] neg_hi:[0,1]
	v_pk_add_f32 v[40:41], v[40:41], v[38:39] op_sel:[0,1] neg_lo:[0,1] neg_hi:[0,1]
	v_pk_add_f32 v[36:37], v[36:37], v[38:39] op_sel:[0,1] neg_lo:[0,1] neg_hi:[0,1]
	v_pk_add_f32 v[38:39], v[42:43], v[38:39] op_sel:[0,1] neg_lo:[0,1] neg_hi:[0,1]
	v_pk_mul_f32 v[36:37], v[36:37], v[44:45] op_sel_hi:[1,0]
	v_pk_mul_f32 v[38:39], v[38:39], v[44:45] op_sel_hi:[1,0]
	v_lshlrev_b32_e32 v42, 16, v30
	v_pk_mul_f32 v[34:35], v[34:35], v[44:45] op_sel_hi:[1,0]
	v_pk_mul_f32 v[40:41], v[40:41], v[44:45] op_sel_hi:[1,0]
	v_pk_mul_f32 v[36:37], v[2:3], v[36:37]
	v_pk_mul_f32 v[38:39], v[4:5], v[38:39]
	v_and_b32_e32 v43, 0xffff0000, v30
	v_add_f32_e32 v44, 0, v42
	v_cvt_pk_bf16_f32 v36, v36, v37
	v_cvt_pk_bf16_f32 v37, v38, v39
	v_lshlrev_b32_e32 v38, 16, v31
	v_add_f32_e32 v44, v44, v43
	v_pk_mul_f32 v[34:35], v[6:7], v[34:35]
	v_pk_mul_f32 v[40:41], v[8:9], v[40:41]
	v_add_f32_e32 v45, v44, v38
	v_mul_f32_e32 v44, v42, v42
	v_cvt_pk_bf16_f32 v34, v34, v35
	v_cvt_pk_bf16_f32 v35, v40, v41
	v_and_b32_e32 v39, 0xffff0000, v31
	v_mov_b32_e32 v30, v38
	v_mov_b32_e32 v31, v42
	v_fmac_f32_e32 v44, v43, v43
	ds_write_b128 v205, v[34:37] offset:8448
	v_lshlrev_b32_e32 v36, 16, v32
	v_pk_fma_f32 v[30:31], v[30:31], v[30:31], v[44:45] op_sel_hi:[1,1,0]
	v_add_f32_e32 v45, v45, v39
	v_mul_f32_e32 v44, v39, v39
	v_and_b32_e32 v37, 0xffff0000, v32
	v_mov_b32_e32 v40, v36
	v_mov_b32_e32 v41, v39
	v_pk_add_f32 v[30:31], v[44:45], v[30:31] op_sel_hi:[0,1]
	v_add_f32_e32 v44, v45, v36
	v_lshlrev_b32_e32 v34, 16, v33
	v_pk_fma_f32 v[30:31], v[40:41], v[40:41], v[30:31]
	v_add_f32_e32 v41, v44, v37
	v_mul_f32_e32 v40, v37, v37
	v_and_b32_e32 v35, 0xffff0000, v33
	v_mov_b32_e32 v32, v34
	v_mov_b32_e32 v33, v37
	v_pk_add_f32 v[30:31], v[40:41], v[30:31] op_sel_hi:[0,1]
	v_pk_fma_f32 v[30:31], v[32:33], v[32:33], v[30:31]
	v_add_f32_e32 v41, v41, v34
	v_mul_f32_e32 v40, v35, v35
	v_mov_b32_e32 v31, v35
	v_pk_add_f32 v[30:31], v[40:41], v[30:31]
	s_nop 1
	v_add_f32_dpp v30, v30, v30 quad_perm:[1,0,3,2] row_mask:0xf bank_mask:0xf
	v_add_f32_dpp v31, v31, v31 quad_perm:[1,0,3,2] row_mask:0xf bank_mask:0xf
	s_nop 0
	v_add_f32_dpp v30, v30, v30 quad_perm:[2,3,0,1] row_mask:0xf bank_mask:0xf
	v_add_f32_dpp v31, v31, v31 quad_perm:[2,3,0,1] row_mask:0xf bank_mask:0xf
	s_nop 0
	v_add_f32_dpp v30, v30, v30 row_half_mirror row_mask:0xf bank_mask:0xf
	v_add_f32_dpp v31, v31, v31 row_half_mirror row_mask:0xf bank_mask:0xf
	s_nop 0
	v_add_f32_dpp v30, v30, v30 row_mirror row_mask:0xf bank_mask:0xf
	v_add_f32_dpp v31, v31, v31 row_mirror row_mask:0xf bank_mask:0xf
	s_nop 0
	v_mov_b32_e32 v32, v30
	v_mov_b32_e32 v33, v31
	s_nop 1
	v_permlane16_swap_b32_e32 v30, v32
	v_permlane16_swap_b32_e32 v31, v33
	s_nop 0
	v_pk_add_f32 v[30:31], v[30:31], v[32:33]
	s_nop 0
	v_pk_mul_f32 v[40:41], v[30:31], s[6:7] op_sel_hi:[1,0]
	s_nop 0
	v_fma_f32 v30, -v41, v41, v40
	v_max_f32_e32 v30, 0, v30
	v_add_f32_e32 v30, 0x3727c5ac, v30
	v_rsq_f32_e32 v44, v30
	v_pk_add_f32 v[30:31], v[42:43], v[40:41] op_sel:[0,1] neg_lo:[0,1] neg_hi:[0,1]
	v_pk_add_f32 v[32:33], v[38:39], v[40:41] op_sel:[0,1] neg_lo:[0,1] neg_hi:[0,1]
	v_pk_add_f32 v[34:35], v[34:35], v[40:41] op_sel:[0,1] neg_lo:[0,1] neg_hi:[0,1]
	v_pk_mul_f32 v[30:31], v[30:31], v[44:45] op_sel_hi:[1,0]
	v_pk_mul_f32 v[32:33], v[32:33], v[44:45] op_sel_hi:[1,0]
	v_pk_mul_f32 v[30:31], v[6:7], v[30:31]
	v_pk_mul_f32 v[32:33], v[8:9], v[32:33]
	v_cvt_pk_bf16_f32 v30, v30, v31
	v_cvt_pk_bf16_f32 v31, v32, v33
	v_pk_add_f32 v[32:33], v[36:37], v[40:41] op_sel:[0,1] neg_lo:[0,1] neg_hi:[0,1]
	v_pk_mul_f32 v[34:35], v[34:35], v[44:45] op_sel_hi:[1,0]
	v_pk_mul_f32 v[32:33], v[32:33], v[44:45] op_sel_hi:[1,0]
	v_lshlrev_b32_e32 v38, 16, v26
	v_pk_mul_f32 v[32:33], v[2:3], v[32:33]
	v_pk_mul_f32 v[34:35], v[4:5], v[34:35]
	v_and_b32_e32 v39, 0xffff0000, v26
	v_add_f32_e32 v40, 0, v38
	v_cvt_pk_bf16_f32 v32, v32, v33
	v_cvt_pk_bf16_f32 v33, v34, v35
	v_lshlrev_b32_e32 v34, 16, v27
	v_add_f32_e32 v40, v40, v39
	v_add_f32_e32 v41, v40, v34
	v_mul_f32_e32 v40, v38, v38
	v_and_b32_e32 v35, 0xffff0000, v27
	v_mov_b32_e32 v26, v34
	v_mov_b32_e32 v27, v38
	v_fmac_f32_e32 v40, v39, v39
	ds_write_b128 v205, v[30:33] offset:16896
	v_lshlrev_b32_e32 v32, 16, v28
	v_pk_fma_f32 v[26:27], v[26:27], v[26:27], v[40:41] op_sel_hi:[1,1,0]
	v_add_f32_e32 v41, v41, v35
	v_mul_f32_e32 v40, v35, v35
	v_and_b32_e32 v33, 0xffff0000, v28
	v_mov_b32_e32 v36, v32
	v_mov_b32_e32 v37, v35
	v_pk_add_f32 v[26:27], v[40:41], v[26:27] op_sel_hi:[0,1]
	v_add_f32_e32 v40, v41, v32
	v_lshlrev_b32_e32 v30, 16, v29
	v_pk_fma_f32 v[26:27], v[36:37], v[36:37], v[26:27]
	v_add_f32_e32 v37, v40, v33
	v_mul_f32_e32 v36, v33, v33
	v_and_b32_e32 v31, 0xffff0000, v29
	v_mov_b32_e32 v28, v30
	v_mov_b32_e32 v29, v33
	v_pk_add_f32 v[26:27], v[36:37], v[26:27] op_sel_hi:[0,1]
	v_pk_fma_f32 v[26:27], v[28:29], v[28:29], v[26:27]
	v_add_f32_e32 v37, v37, v30
	v_mul_f32_e32 v36, v31, v31
	v_mov_b32_e32 v27, v31
	v_pk_add_f32 v[26:27], v[36:37], v[26:27]
	s_nop 1
	v_add_f32_dpp v26, v26, v26 quad_perm:[1,0,3,2] row_mask:0xf bank_mask:0xf
	v_add_f32_dpp v27, v27, v27 quad_perm:[1,0,3,2] row_mask:0xf bank_mask:0xf
	s_nop 0
	v_add_f32_dpp v26, v26, v26 quad_perm:[2,3,0,1] row_mask:0xf bank_mask:0xf
	v_add_f32_dpp v27, v27, v27 quad_perm:[2,3,0,1] row_mask:0xf bank_mask:0xf
	s_nop 0
	v_add_f32_dpp v26, v26, v26 row_half_mirror row_mask:0xf bank_mask:0xf
	v_add_f32_dpp v27, v27, v27 row_half_mirror row_mask:0xf bank_mask:0xf
	s_nop 0
	v_add_f32_dpp v26, v26, v26 row_mirror row_mask:0xf bank_mask:0xf
	v_add_f32_dpp v27, v27, v27 row_mirror row_mask:0xf bank_mask:0xf
	s_nop 0
	v_mov_b32_e32 v28, v26
	v_mov_b32_e32 v29, v27
	s_nop 1
	v_permlane16_swap_b32_e32 v26, v28
	v_permlane16_swap_b32_e32 v27, v29
	s_nop 0
	v_pk_add_f32 v[26:27], v[26:27], v[28:29]
	s_nop 0
	v_pk_mul_f32 v[36:37], v[26:27], s[6:7] op_sel_hi:[1,0]
	s_nop 0
	v_fma_f32 v26, -v37, v37, v36
	v_max_f32_e32 v26, 0, v26
	v_add_f32_e32 v26, 0x3727c5ac, v26
	v_rsq_f32_e32 v40, v26
	v_pk_add_f32 v[26:27], v[38:39], v[36:37] op_sel:[0,1] neg_lo:[0,1] neg_hi:[0,1]
	v_pk_add_f32 v[28:29], v[34:35], v[36:37] op_sel:[0,1] neg_lo:[0,1] neg_hi:[0,1]
	v_pk_add_f32 v[30:31], v[30:31], v[36:37] op_sel:[0,1] neg_lo:[0,1] neg_hi:[0,1]
	v_pk_mul_f32 v[26:27], v[26:27], v[40:41] op_sel_hi:[1,0]
	v_pk_mul_f32 v[28:29], v[28:29], v[40:41] op_sel_hi:[1,0]
	v_pk_mul_f32 v[26:27], v[6:7], v[26:27]
	v_pk_mul_f32 v[28:29], v[8:9], v[28:29]
	v_cvt_pk_bf16_f32 v26, v26, v27
	v_cvt_pk_bf16_f32 v27, v28, v29
	v_pk_add_f32 v[28:29], v[32:33], v[36:37] op_sel:[0,1] neg_lo:[0,1] neg_hi:[0,1]
	v_pk_mul_f32 v[30:31], v[30:31], v[40:41] op_sel_hi:[1,0]
	v_pk_mul_f32 v[28:29], v[28:29], v[40:41] op_sel_hi:[1,0]
	v_lshlrev_b32_e32 v34, 16, v22
	v_pk_mul_f32 v[28:29], v[2:3], v[28:29]
	v_pk_mul_f32 v[30:31], v[4:5], v[30:31]
	v_and_b32_e32 v35, 0xffff0000, v22
	v_add_f32_e32 v36, 0, v34
	v_cvt_pk_bf16_f32 v28, v28, v29
	v_cvt_pk_bf16_f32 v29, v30, v31
	v_lshlrev_b32_e32 v30, 16, v23
	v_add_f32_e32 v36, v36, v35
	v_add_f32_e32 v37, v36, v30
	v_mul_f32_e32 v36, v34, v34
	v_and_b32_e32 v31, 0xffff0000, v23
	v_mov_b32_e32 v22, v30
	v_mov_b32_e32 v23, v34
	v_fmac_f32_e32 v36, v35, v35
	ds_write_b128 v205, v[26:29] offset:25344
	v_lshlrev_b32_e32 v28, 16, v24
	v_pk_fma_f32 v[22:23], v[22:23], v[22:23], v[36:37] op_sel_hi:[1,1,0]
	v_add_f32_e32 v37, v37, v31
	v_mul_f32_e32 v36, v31, v31
	v_and_b32_e32 v29, 0xffff0000, v24
	v_mov_b32_e32 v32, v28
	v_mov_b32_e32 v33, v31
	v_pk_add_f32 v[22:23], v[36:37], v[22:23] op_sel_hi:[0,1]
	v_add_f32_e32 v36, v37, v28
	v_lshlrev_b32_e32 v26, 16, v25
	v_pk_fma_f32 v[22:23], v[32:33], v[32:33], v[22:23]
	v_add_f32_e32 v33, v36, v29
	v_mul_f32_e32 v32, v29, v29
	v_and_b32_e32 v27, 0xffff0000, v25
	v_mov_b32_e32 v24, v26
	v_mov_b32_e32 v25, v29
	v_pk_add_f32 v[22:23], v[32:33], v[22:23] op_sel_hi:[0,1]
	v_pk_fma_f32 v[22:23], v[24:25], v[24:25], v[22:23]
	v_add_f32_e32 v33, v33, v26
	v_mul_f32_e32 v32, v27, v27
	v_mov_b32_e32 v23, v27
	v_pk_add_f32 v[22:23], v[32:33], v[22:23]
	s_nop 1
	v_add_f32_dpp v22, v22, v22 quad_perm:[1,0,3,2] row_mask:0xf bank_mask:0xf
	v_add_f32_dpp v23, v23, v23 quad_perm:[1,0,3,2] row_mask:0xf bank_mask:0xf
	s_nop 0
	v_add_f32_dpp v22, v22, v22 quad_perm:[2,3,0,1] row_mask:0xf bank_mask:0xf
	v_add_f32_dpp v23, v23, v23 quad_perm:[2,3,0,1] row_mask:0xf bank_mask:0xf
	s_nop 0
	v_add_f32_dpp v22, v22, v22 row_half_mirror row_mask:0xf bank_mask:0xf
	v_add_f32_dpp v23, v23, v23 row_half_mirror row_mask:0xf bank_mask:0xf
	s_nop 0
	v_add_f32_dpp v22, v22, v22 row_mirror row_mask:0xf bank_mask:0xf
	v_add_f32_dpp v23, v23, v23 row_mirror row_mask:0xf bank_mask:0xf
	s_nop 0
	v_mov_b32_e32 v24, v22
	v_mov_b32_e32 v25, v23
	s_nop 1
	v_permlane16_swap_b32_e32 v22, v24
	v_permlane16_swap_b32_e32 v23, v25
	s_nop 0
	v_pk_add_f32 v[22:23], v[22:23], v[24:25]
	s_nop 0
	v_pk_mul_f32 v[32:33], v[22:23], s[6:7] op_sel_hi:[1,0]
	s_nop 0
	v_fma_f32 v22, -v33, v33, v32
	v_max_f32_e32 v22, 0, v22
	v_add_f32_e32 v22, 0x3727c5ac, v22
	v_rsq_f32_e32 v36, v22
	v_pk_add_f32 v[22:23], v[34:35], v[32:33] op_sel:[0,1] neg_lo:[0,1] neg_hi:[0,1]
	v_pk_add_f32 v[24:25], v[30:31], v[32:33] op_sel:[0,1] neg_lo:[0,1] neg_hi:[0,1]
	v_pk_add_f32 v[26:27], v[26:27], v[32:33] op_sel:[0,1] neg_lo:[0,1] neg_hi:[0,1]
	v_pk_mul_f32 v[22:23], v[22:23], v[36:37] op_sel_hi:[1,0]
	v_pk_mul_f32 v[24:25], v[24:25], v[36:37] op_sel_hi:[1,0]
	v_pk_mul_f32 v[22:23], v[6:7], v[22:23]
	v_pk_mul_f32 v[24:25], v[8:9], v[24:25]
	v_cvt_pk_bf16_f32 v22, v22, v23
	v_cvt_pk_bf16_f32 v23, v24, v25
	v_pk_add_f32 v[24:25], v[28:29], v[32:33] op_sel:[0,1] neg_lo:[0,1] neg_hi:[0,1]
	v_pk_mul_f32 v[26:27], v[26:27], v[36:37] op_sel_hi:[1,0]
	v_pk_mul_f32 v[24:25], v[24:25], v[36:37] op_sel_hi:[1,0]
	v_lshlrev_b32_e32 v30, 16, v18
	v_pk_mul_f32 v[24:25], v[2:3], v[24:25]
	v_pk_mul_f32 v[26:27], v[4:5], v[26:27]
	v_and_b32_e32 v31, 0xffff0000, v18
	v_add_f32_e32 v32, 0, v30
	v_cvt_pk_bf16_f32 v24, v24, v25
	v_cvt_pk_bf16_f32 v25, v26, v27
	v_lshlrev_b32_e32 v26, 16, v19
	v_add_f32_e32 v32, v32, v31
	v_add_f32_e32 v33, v32, v26
	v_mul_f32_e32 v32, v30, v30
	v_and_b32_e32 v27, 0xffff0000, v19
	v_mov_b32_e32 v18, v26
	v_mov_b32_e32 v19, v30
	v_fmac_f32_e32 v32, v31, v31
	ds_write_b128 v205, v[22:25] offset:33792
	v_lshlrev_b32_e32 v24, 16, v20
	v_pk_fma_f32 v[18:19], v[18:19], v[18:19], v[32:33] op_sel_hi:[1,1,0]
	v_add_f32_e32 v33, v33, v27
	v_mul_f32_e32 v32, v27, v27
	v_and_b32_e32 v25, 0xffff0000, v20
	v_mov_b32_e32 v28, v24
	v_mov_b32_e32 v29, v27
	v_pk_add_f32 v[18:19], v[32:33], v[18:19] op_sel_hi:[0,1]
	v_add_f32_e32 v32, v33, v24
	v_lshlrev_b32_e32 v22, 16, v21
	v_pk_fma_f32 v[18:19], v[28:29], v[28:29], v[18:19]
	v_add_f32_e32 v29, v32, v25
	v_mul_f32_e32 v28, v25, v25
	v_and_b32_e32 v23, 0xffff0000, v21
	v_mov_b32_e32 v20, v22
	v_mov_b32_e32 v21, v25
	v_pk_add_f32 v[18:19], v[28:29], v[18:19] op_sel_hi:[0,1]
	v_pk_fma_f32 v[18:19], v[20:21], v[20:21], v[18:19]
	v_add_f32_e32 v29, v29, v22
	v_mul_f32_e32 v28, v23, v23
	v_mov_b32_e32 v19, v23
	v_pk_add_f32 v[18:19], v[28:29], v[18:19]
	s_nop 1
	v_add_f32_dpp v18, v18, v18 quad_perm:[1,0,3,2] row_mask:0xf bank_mask:0xf
	v_add_f32_dpp v19, v19, v19 quad_perm:[1,0,3,2] row_mask:0xf bank_mask:0xf
	s_nop 0
	v_add_f32_dpp v18, v18, v18 quad_perm:[2,3,0,1] row_mask:0xf bank_mask:0xf
	v_add_f32_dpp v19, v19, v19 quad_perm:[2,3,0,1] row_mask:0xf bank_mask:0xf
	s_nop 0
	v_add_f32_dpp v18, v18, v18 row_half_mirror row_mask:0xf bank_mask:0xf
	v_add_f32_dpp v19, v19, v19 row_half_mirror row_mask:0xf bank_mask:0xf
	s_nop 0
	v_add_f32_dpp v18, v18, v18 row_mirror row_mask:0xf bank_mask:0xf
	v_add_f32_dpp v19, v19, v19 row_mirror row_mask:0xf bank_mask:0xf
	s_nop 0
	v_mov_b32_e32 v20, v18
	v_mov_b32_e32 v21, v19
	s_nop 1
	v_permlane16_swap_b32_e32 v18, v20
	v_permlane16_swap_b32_e32 v19, v21
	s_nop 0
	v_pk_add_f32 v[18:19], v[18:19], v[20:21]
	s_nop 0
	v_pk_mul_f32 v[28:29], v[18:19], s[6:7] op_sel_hi:[1,0]
	s_nop 0
	v_fma_f32 v18, -v29, v29, v28
	v_max_f32_e32 v18, 0, v18
	v_add_f32_e32 v18, 0x3727c5ac, v18
	v_rsq_f32_e32 v32, v18
	v_pk_add_f32 v[18:19], v[30:31], v[28:29] op_sel:[0,1] neg_lo:[0,1] neg_hi:[0,1]
	v_pk_add_f32 v[20:21], v[26:27], v[28:29] op_sel:[0,1] neg_lo:[0,1] neg_hi:[0,1]
	v_pk_add_f32 v[22:23], v[22:23], v[28:29] op_sel:[0,1] neg_lo:[0,1] neg_hi:[0,1]
	v_pk_mul_f32 v[18:19], v[18:19], v[32:33] op_sel_hi:[1,0]
	v_pk_mul_f32 v[20:21], v[20:21], v[32:33] op_sel_hi:[1,0]
	v_pk_mul_f32 v[18:19], v[6:7], v[18:19]
	v_pk_mul_f32 v[20:21], v[8:9], v[20:21]
	v_cvt_pk_bf16_f32 v18, v18, v19
	v_cvt_pk_bf16_f32 v19, v20, v21
	v_pk_add_f32 v[20:21], v[24:25], v[28:29] op_sel:[0,1] neg_lo:[0,1] neg_hi:[0,1]
	v_pk_mul_f32 v[22:23], v[22:23], v[32:33] op_sel_hi:[1,0]
	v_pk_mul_f32 v[20:21], v[20:21], v[32:33] op_sel_hi:[1,0]
	v_lshlrev_b32_e32 v26, 16, v14
	v_pk_mul_f32 v[20:21], v[2:3], v[20:21]
	v_pk_mul_f32 v[22:23], v[4:5], v[22:23]
	v_and_b32_e32 v27, 0xffff0000, v14
	v_add_f32_e32 v28, 0, v26
	v_cvt_pk_bf16_f32 v20, v20, v21
	v_cvt_pk_bf16_f32 v21, v22, v23
	v_lshlrev_b32_e32 v22, 16, v15
	v_add_f32_e32 v28, v28, v27
	v_add_f32_e32 v29, v28, v22
	v_mul_f32_e32 v28, v26, v26
	v_and_b32_e32 v23, 0xffff0000, v15
	v_mov_b32_e32 v14, v22
	v_mov_b32_e32 v15, v26
	v_fmac_f32_e32 v28, v27, v27
	ds_write_b128 v205, v[18:21] offset:42240
	v_lshlrev_b32_e32 v20, 16, v16
	v_pk_fma_f32 v[14:15], v[14:15], v[14:15], v[28:29] op_sel_hi:[1,1,0]
	v_add_f32_e32 v29, v29, v23
	v_mul_f32_e32 v28, v23, v23
	v_and_b32_e32 v21, 0xffff0000, v16
	v_mov_b32_e32 v24, v20
	v_mov_b32_e32 v25, v23
	v_pk_add_f32 v[14:15], v[28:29], v[14:15] op_sel_hi:[0,1]
	v_add_f32_e32 v28, v29, v20
	v_lshlrev_b32_e32 v18, 16, v17
	v_pk_fma_f32 v[14:15], v[24:25], v[24:25], v[14:15]
	v_add_f32_e32 v25, v28, v21
	v_mul_f32_e32 v24, v21, v21
	v_and_b32_e32 v19, 0xffff0000, v17
	v_mov_b32_e32 v16, v18
	v_mov_b32_e32 v17, v21
	v_pk_add_f32 v[14:15], v[24:25], v[14:15] op_sel_hi:[0,1]
	v_pk_fma_f32 v[14:15], v[16:17], v[16:17], v[14:15]
	v_add_f32_e32 v25, v25, v18
	v_mul_f32_e32 v24, v19, v19
	v_mov_b32_e32 v15, v19
	v_pk_add_f32 v[14:15], v[24:25], v[14:15]
	s_nop 1
	v_add_f32_dpp v14, v14, v14 quad_perm:[1,0,3,2] row_mask:0xf bank_mask:0xf
	v_add_f32_dpp v15, v15, v15 quad_perm:[1,0,3,2] row_mask:0xf bank_mask:0xf
	s_nop 0
	v_add_f32_dpp v14, v14, v14 quad_perm:[2,3,0,1] row_mask:0xf bank_mask:0xf
	v_add_f32_dpp v15, v15, v15 quad_perm:[2,3,0,1] row_mask:0xf bank_mask:0xf
	s_nop 0
	v_add_f32_dpp v14, v14, v14 row_half_mirror row_mask:0xf bank_mask:0xf
	v_add_f32_dpp v15, v15, v15 row_half_mirror row_mask:0xf bank_mask:0xf
	s_nop 0
	v_add_f32_dpp v14, v14, v14 row_mirror row_mask:0xf bank_mask:0xf
	v_add_f32_dpp v15, v15, v15 row_mirror row_mask:0xf bank_mask:0xf
	s_nop 0
	v_mov_b32_e32 v16, v14
	v_mov_b32_e32 v17, v15
	s_nop 1
	v_permlane16_swap_b32_e32 v14, v16
	v_permlane16_swap_b32_e32 v15, v17
	s_nop 0
	v_pk_add_f32 v[14:15], v[14:15], v[16:17]
	s_nop 0
	v_pk_mul_f32 v[24:25], v[14:15], s[6:7] op_sel_hi:[1,0]
	s_nop 0
	v_fma_f32 v14, -v25, v25, v24
	v_max_f32_e32 v14, 0, v14
	v_add_f32_e32 v14, 0x3727c5ac, v14
	v_rsq_f32_e32 v28, v14
	v_pk_add_f32 v[14:15], v[26:27], v[24:25] op_sel:[0,1] neg_lo:[0,1] neg_hi:[0,1]
	v_pk_add_f32 v[16:17], v[22:23], v[24:25] op_sel:[0,1] neg_lo:[0,1] neg_hi:[0,1]
	v_pk_add_f32 v[18:19], v[18:19], v[24:25] op_sel:[0,1] neg_lo:[0,1] neg_hi:[0,1]
	v_pk_mul_f32 v[14:15], v[14:15], v[28:29] op_sel_hi:[1,0]
	v_pk_mul_f32 v[16:17], v[16:17], v[28:29] op_sel_hi:[1,0]
	v_pk_mul_f32 v[14:15], v[6:7], v[14:15]
	v_pk_mul_f32 v[16:17], v[8:9], v[16:17]
	v_cvt_pk_bf16_f32 v14, v14, v15
	v_cvt_pk_bf16_f32 v15, v16, v17
	v_pk_add_f32 v[16:17], v[20:21], v[24:25] op_sel:[0,1] neg_lo:[0,1] neg_hi:[0,1]
	v_pk_mul_f32 v[18:19], v[18:19], v[28:29] op_sel_hi:[1,0]
	v_pk_mul_f32 v[16:17], v[16:17], v[28:29] op_sel_hi:[1,0]
	v_lshlrev_b32_e32 v22, 16, v10
	v_pk_mul_f32 v[16:17], v[2:3], v[16:17]
	v_pk_mul_f32 v[18:19], v[4:5], v[18:19]
	v_and_b32_e32 v23, 0xffff0000, v10
	v_add_f32_e32 v24, 0, v22
	v_cvt_pk_bf16_f32 v16, v16, v17
	v_cvt_pk_bf16_f32 v17, v18, v19
	v_lshlrev_b32_e32 v18, 16, v11
	v_add_f32_e32 v24, v24, v23
	v_add_f32_e32 v25, v24, v18
	v_mul_f32_e32 v24, v22, v22
	v_and_b32_e32 v19, 0xffff0000, v11
	v_mov_b32_e32 v10, v18
	v_mov_b32_e32 v11, v22
	v_fmac_f32_e32 v24, v23, v23
	ds_write_b128 v205, v[14:17] offset:50688
	v_lshlrev_b32_e32 v16, 16, v12
	v_pk_fma_f32 v[10:11], v[10:11], v[10:11], v[24:25] op_sel_hi:[1,1,0]
	v_add_f32_e32 v25, v25, v19
	v_mul_f32_e32 v24, v19, v19
	v_and_b32_e32 v17, 0xffff0000, v12
	v_mov_b32_e32 v20, v16
	v_mov_b32_e32 v21, v19
	v_pk_add_f32 v[10:11], v[24:25], v[10:11] op_sel_hi:[0,1]
	v_add_f32_e32 v24, v25, v16
	v_lshlrev_b32_e32 v14, 16, v13
	v_pk_fma_f32 v[10:11], v[20:21], v[20:21], v[10:11]
	v_add_f32_e32 v21, v24, v17
	v_mul_f32_e32 v20, v17, v17
	v_and_b32_e32 v15, 0xffff0000, v13
	v_mov_b32_e32 v12, v14
	v_mov_b32_e32 v13, v17
	v_pk_add_f32 v[10:11], v[20:21], v[10:11] op_sel_hi:[0,1]
	v_pk_fma_f32 v[10:11], v[12:13], v[12:13], v[10:11]
	v_add_f32_e32 v21, v21, v14
	v_mul_f32_e32 v20, v15, v15
	v_mov_b32_e32 v11, v15
	v_pk_add_f32 v[10:11], v[20:21], v[10:11]
	s_nop 1
	v_add_f32_dpp v10, v10, v10 quad_perm:[1,0,3,2] row_mask:0xf bank_mask:0xf
	v_add_f32_dpp v11, v11, v11 quad_perm:[1,0,3,2] row_mask:0xf bank_mask:0xf
	s_nop 0
	v_add_f32_dpp v10, v10, v10 quad_perm:[2,3,0,1] row_mask:0xf bank_mask:0xf
	v_add_f32_dpp v11, v11, v11 quad_perm:[2,3,0,1] row_mask:0xf bank_mask:0xf
	s_nop 0
	v_add_f32_dpp v10, v10, v10 row_half_mirror row_mask:0xf bank_mask:0xf
	v_add_f32_dpp v11, v11, v11 row_half_mirror row_mask:0xf bank_mask:0xf
	s_nop 0
	v_add_f32_dpp v10, v10, v10 row_mirror row_mask:0xf bank_mask:0xf
	v_add_f32_dpp v11, v11, v11 row_mirror row_mask:0xf bank_mask:0xf
	s_nop 0
	v_mov_b32_e32 v12, v10
	v_mov_b32_e32 v13, v11
	s_nop 1
	v_permlane16_swap_b32_e32 v10, v12
	v_permlane16_swap_b32_e32 v11, v13
	s_nop 0
	v_pk_add_f32 v[10:11], v[10:11], v[12:13]
	s_nop 0
	v_pk_mul_f32 v[10:11], v[10:11], s[6:7] op_sel_hi:[1,0]
	s_nop 0
	v_fma_f32 v12, -v11, v11, v10
	v_max_f32_e32 v12, 0, v12
	v_add_f32_e32 v12, 0x3727c5ac, v12
	v_rsq_f32_e32 v12, v12
	v_pk_add_f32 v[20:21], v[22:23], v[10:11] op_sel:[0,1] neg_lo:[0,1] neg_hi:[0,1]
	v_pk_add_f32 v[18:19], v[18:19], v[10:11] op_sel:[0,1] neg_lo:[0,1] neg_hi:[0,1]
	v_pk_mul_f32 v[20:21], v[20:21], v[12:13] op_sel_hi:[1,0]
	v_pk_mul_f32 v[18:19], v[18:19], v[12:13] op_sel_hi:[1,0]
	v_pk_mul_f32 v[6:7], v[6:7], v[20:21]
	v_pk_mul_f32 v[8:9], v[8:9], v[18:19]
	v_cvt_pk_bf16_f32 v6, v6, v7
	v_cvt_pk_bf16_f32 v7, v8, v9
	v_pk_add_f32 v[8:9], v[16:17], v[10:11] op_sel:[0,1] neg_lo:[0,1] neg_hi:[0,1]
	s_nop 0
	v_pk_mul_f32 v[8:9], v[8:9], v[12:13] op_sel_hi:[1,0]
	s_nop 0
	v_pk_mul_f32 v[2:3], v[2:3], v[8:9]
	s_nop 0
	v_cvt_pk_bf16_f32 v8, v2, v3
	v_pk_add_f32 v[2:3], v[14:15], v[10:11] op_sel:[0,1] neg_lo:[0,1] neg_hi:[0,1]
	s_nop 0
	v_pk_mul_f32 v[2:3], v[2:3], v[12:13] op_sel_hi:[1,0]
	s_nop 0
	v_pk_mul_f32 v[2:3], v[4:5], v[2:3]
	s_nop 0
	v_cvt_pk_bf16_f32 v9, v2, v3
	ds_write_b128 v205, v[6:9] offset:59136
	global_load_dwordx4 v[50:53], v[184:185], off offset:512
	global_load_dwordx4 v[38:41], v[182:183], off offset:512
	global_load_dwordx4 v[34:37], v[180:181], off offset:512
	global_load_dwordx4 v[22:25], v[178:179], off offset:512
	global_load_dwordx4 v[18:21], v[176:177], off offset:512
	global_load_dwordx4 v[10:13], v[174:175], off offset:512
	global_load_dwordx4 v[6:9], v[172:173], off offset:512
	global_load_dwordx4 v[2:5], v[170:171], off offset:512
	global_load_dwordx4 v[94:97], v[156:157], off
	global_load_dwordx4 v[90:93], v[156:157], off offset:64
	global_load_dwordx4 v[86:89], v[156:157], off offset:128
	global_load_dwordx4 v[82:85], v[156:157], off offset:192
	global_load_dword v212, v[158:159], off
	global_load_dwordx4 v[78:81], v[160:161], off
	global_load_dwordx4 v[74:77], v[160:161], off offset:64
	global_load_dwordx4 v[70:73], v[160:161], off offset:128
	global_load_dwordx4 v[66:69], v[160:161], off offset:192
	global_load_dword v211, v[162:163], off offset:64
	global_load_dwordx4 v[62:65], v[164:165], off
	global_load_dwordx4 v[58:61], v[164:165], off offset:64
	global_load_dwordx4 v[54:57], v[164:165], off offset:128
	global_load_dwordx4 v[46:49], v[164:165], off offset:192
	global_load_dword v210, v[162:163], off offset:128
	global_load_dwordx4 v[42:45], v[166:167], off
	global_load_dwordx4 v[30:33], v[166:167], off offset:64
	global_load_dwordx4 v[26:29], v[166:167], off offset:128
	global_load_dwordx4 v[14:17], v[166:167], off offset:192
	global_load_dword v209, v[162:163], off offset:192
	s_waitcnt lgkmcnt(0)
	s_barrier
	ds_read_b64_tr_b16 v[98:99], v206
	ds_read_b64_tr_b16 v[100:101], v206 offset:2112
	ds_read_b64_tr_b16 v[112:113], v206 offset:2144
	ds_read_b64_tr_b16 v[110:111], v206 offset:32
	ds_read_b64_tr_b16 v[106:107], v206 offset:64
	ds_read_b64_tr_b16 v[102:103], v206 offset:96
	ds_read_b64_tr_b16 v[108:109], v206 offset:2176
	ds_read_b64_tr_b16 v[104:105], v206 offset:2208
	ds_read_b64_tr_b16 v[118:119], v206 offset:16896
	s_waitcnt vmcnt(19) lgkmcnt(7)
	v_mfma_f32_16x16x32_bf16 v[114:117], v[98:101], v[94:97], 0
	ds_read_b64_tr_b16 v[120:121], v206 offset:19008
	ds_read_b64_tr_b16 v[124:125], v206 offset:19040
	s_waitcnt lgkmcnt(7)
	v_mfma_f32_16x16x32_bf16 v[130:133], v[110:113], v[94:97], 0
	s_waitcnt lgkmcnt(4)
	v_mfma_f32_16x16x32_bf16 v[136:139], v[106:109], v[94:97], 0
	s_waitcnt lgkmcnt(3)
	v_mfma_f32_16x16x32_bf16 v[140:143], v[102:105], v[94:97], 0
	ds_read_b64_tr_b16 v[122:123], v206 offset:16928
	ds_read_b64_tr_b16 v[126:127], v206 offset:16960
	ds_read_b64_tr_b16 v[94:95], v206 offset:16992
	ds_read_b64_tr_b16 v[128:129], v206 offset:19072
	ds_read_b64_tr_b16 v[96:97], v206 offset:19104
	ds_read_b64_tr_b16 v[134:135], v206 offset:33792
	s_waitcnt vmcnt(18) lgkmcnt(7)
	v_mfma_f32_16x16x32_bf16 v[144:147], v[118:121], v[90:93], v[114:117]
	s_waitcnt lgkmcnt(5)
	v_mfma_f32_16x16x32_bf16 v[214:217], v[122:125], v[90:93], v[130:133]
	s_waitcnt lgkmcnt(2)
	v_mfma_f32_16x16x32_bf16 v[218:221], v[126:129], v[90:93], v[136:139]
	s_nop 2
	ds_read_b64_tr_b16 v[136:137], v206 offset:35904
	ds_read_b64_tr_b16 v[132:133], v206 offset:35936
	s_waitcnt lgkmcnt(3)
	v_mfma_f32_16x16x32_bf16 v[138:141], v[94:97], v[90:93], v[140:143]
	ds_read_b64_tr_b16 v[130:131], v206 offset:33824
	ds_read_b64_tr_b16 v[114:115], v206 offset:33856
	ds_read_b64_tr_b16 v[90:91], v206 offset:33888
	ds_read_b64_tr_b16 v[116:117], v206 offset:35968
	ds_read_b64_tr_b16 v[92:93], v206 offset:36000
	s_waitcnt vmcnt(17) lgkmcnt(6)
	v_mfma_f32_16x16x32_bf16 v[222:225], v[134:137], v[86:89], v[144:147]
	s_nop 2
	ds_read_b64_tr_b16 v[146:147], v206 offset:50688
	s_waitcnt lgkmcnt(5)
	v_mfma_f32_16x16x32_bf16 v[214:217], v[130:133], v[86:89], v[214:217]
	ds_read_b64_tr_b16 v[148:149], v206 offset:52800
	ds_read_b64_tr_b16 v[144:145], v206 offset:52832
	s_waitcnt lgkmcnt(4)
	v_mfma_f32_16x16x32_bf16 v[218:221], v[114:117], v[86:89], v[218:221]
	s_waitcnt lgkmcnt(3)
	v_mfma_f32_16x16x32_bf16 v[226:229], v[90:93], v[86:89], v[138:141]
	ds_read_b64_tr_b16 v[142:143], v206 offset:50720
	s_nop 1
	ds_read_b64_tr_b16 v[138:139], v206 offset:50752
	ds_read_b64_tr_b16 v[86:87], v206 offset:50784
	ds_read_b64_tr_b16 v[140:141], v206 offset:52864
	ds_read_b64_tr_b16 v[88:89], v206 offset:52896
	s_waitcnt vmcnt(16) lgkmcnt(6)
	v_mfma_f32_16x16x32_bf16 v[222:225], v[146:149], v[82:85], v[222:225]
	s_waitcnt lgkmcnt(4)
	v_mfma_f32_16x16x32_bf16 v[214:217], v[142:145], v[82:85], v[214:217]
	s_waitcnt lgkmcnt(1)
	v_mfma_f32_16x16x32_bf16 v[218:221], v[138:141], v[82:85], v[218:221]
	s_waitcnt vmcnt(15)
	s_nop 2
	v_add_f32_e32 v213, v212, v222
	v_add_f32_e32 v222, v212, v223
	v_cvt_pk_f16_f32 v230, v213, v222
	s_waitcnt lgkmcnt(0)
	v_mfma_f32_16x16x32_bf16 v[82:85], v[86:89], v[82:85], v[226:229]
	v_add_f32_e32 v213, v212, v224
	s_waitcnt vmcnt(14)
	v_mfma_f32_16x16x32_bf16 v[226:229], v[98:101], v[78:81], 0
	v_mfma_f32_16x16x32_bf16 v[240:243], v[110:113], v[78:81], 0
	s_nop 3
	v_add_f32_e32 v82, v212, v82
	v_add_f32_e32 v83, v212, v83
	v_mfma_f32_16x16x32_bf16 v[244:247], v[106:109], v[78:81], 0
	v_mfma_f32_16x16x32_bf16 v[78:81], v[102:105], v[78:81], 0
	s_waitcnt vmcnt(13)
	v_mfma_f32_16x16x32_bf16 v[226:229], v[118:121], v[74:77], v[226:229]
	v_mfma_f32_16x16x32_bf16 v[240:243], v[122:125], v[74:77], v[240:243]
	v_mfma_f32_16x16x32_bf16 v[244:247], v[126:129], v[74:77], v[244:247]
	v_mfma_f32_16x16x32_bf16 v[74:77], v[94:97], v[74:77], v[78:81]
	s_waitcnt vmcnt(12)
	v_mfma_f32_16x16x32_bf16 v[78:81], v[134:137], v[70:73], v[226:229]
	v_mfma_f32_16x16x32_bf16 v[226:229], v[130:133], v[70:73], v[240:243]
	v_mfma_f32_16x16x32_bf16 v[240:243], v[114:117], v[70:73], v[244:247]
	v_mfma_f32_16x16x32_bf16 v[70:73], v[90:93], v[70:73], v[74:77]
	s_waitcnt vmcnt(11)
	v_mfma_f32_16x16x32_bf16 v[74:77], v[146:149], v[66:69], v[78:81]
	v_mfma_f32_16x16x32_bf16 v[78:81], v[142:145], v[66:69], v[226:229]
	v_mfma_f32_16x16x32_bf16 v[226:229], v[138:141], v[66:69], v[240:243]
	s_waitcnt vmcnt(10)
	s_nop 4
	v_add_f32_e32 v74, v211, v74
	v_add_f32_e32 v75, v211, v75
	v_mfma_f32_16x16x32_bf16 v[66:69], v[86:89], v[66:69], v[70:73]
	v_cvt_pk_f16_f32 v240, v82, v83
	v_add_f32_e32 v82, v212, v84
	v_add_f32_e32 v83, v212, v85
	v_add_f32_e32 v70, v212, v225
	v_cvt_pk_f16_f32 v231, v213, v70
	v_add_f32_e32 v213, v212, v214
	v_add_f32_e32 v214, v212, v215
	v_cvt_pk_f16_f32 v214, v213, v214
	v_add_f32_e32 v213, v212, v216
	v_add_f32_e32 v215, v212, v217
	s_waitcnt vmcnt(9)
	v_mfma_f32_16x16x32_bf16 v[70:73], v[98:101], v[62:65], 0
	v_cvt_pk_f16_f32 v215, v213, v215
	ds_write2_b64 v207, v[230:231], v[214:215] offset1:4
	v_add_f32_e32 v213, v212, v218
	v_mfma_f32_16x16x32_bf16 v[222:225], v[110:113], v[62:65], 0
	v_add_f32_e32 v218, v212, v219
	v_cvt_pk_f16_f32 v230, v213, v218
	v_add_f32_e32 v213, v212, v220
	v_mfma_f32_16x16x32_bf16 v[214:217], v[106:109], v[62:65], 0
	v_add_f32_e32 v218, v212, v221
	v_cvt_pk_f16_f32 v231, v213, v218
	v_cvt_pk_f16_f32 v241, v82, v83
	v_mfma_f32_16x16x32_bf16 v[62:65], v[102:105], v[62:65], 0
	v_cvt_pk_f16_f32 v212, v74, v75
	v_add_f32_e32 v74, v211, v76
	v_add_f32_e32 v75, v211, v77
	s_waitcnt vmcnt(8)
	v_mfma_f32_16x16x32_bf16 v[70:73], v[118:121], v[58:61], v[70:73]
	v_cvt_pk_f16_f32 v213, v74, v75
	v_add_f32_e32 v74, v211, v78
	v_add_f32_e32 v75, v211, v79
	v_mfma_f32_16x16x32_bf16 v[218:221], v[122:125], v[58:61], v[222:225]
	v_cvt_pk_f16_f32 v78, v74, v75
	v_add_f32_e32 v79, v211, v80
	v_add_f32_e32 v80, v211, v81
	v_mfma_f32_16x16x32_bf16 v[82:85], v[126:129], v[58:61], v[214:217]
	v_cvt_pk_f16_f32 v79, v79, v80
	v_add_u32_e32 v80, 0x2000, v207
	ds_write2_b64 v80, v[212:213], v[78:79] offset0:32 offset1:36
	v_mfma_f32_16x16x32_bf16 v[58:61], v[94:97], v[58:61], v[62:65]
	v_add_f32_e32 v66, v211, v66
	v_add_f32_e32 v67, v211, v67
	v_cvt_pk_f16_f32 v66, v66, v67
	s_waitcnt vmcnt(7)
	v_mfma_f32_16x16x32_bf16 v[62:65], v[134:137], v[54:57], v[70:73]
	v_add_f32_e32 v67, v211, v68
	v_add_f32_e32 v68, v211, v69
	v_cvt_pk_f16_f32 v67, v67, v68
	v_mfma_f32_16x16x32_bf16 v[70:73], v[130:133], v[54:57], v[218:221]
	ds_write2_b64 v207, v[230:231], v[240:241] offset0:8 offset1:12
	v_mfma_f32_16x16x32_bf16 v[74:77], v[114:117], v[54:57], v[82:85]
	v_mfma_f32_16x16x32_bf16 v[54:57], v[90:93], v[54:57], v[58:61]
	s_nop 2
	v_add_f32_e32 v58, v211, v226
	v_add_f32_e32 v59, v211, v227
	v_cvt_pk_f16_f32 v78, v58, v59
	s_waitcnt vmcnt(6)
	v_mfma_f32_16x16x32_bf16 v[58:61], v[146:149], v[46:49], v[62:65]
	s_nop 2
	v_add_f32_e32 v62, v211, v228
	v_add_f32_e32 v63, v211, v229
	v_cvt_pk_f16_f32 v79, v62, v63
	v_mfma_f32_16x16x32_bf16 v[62:65], v[142:145], v[46:49], v[70:73]
	ds_write2_b64 v80, v[78:79], v[66:67] offset0:40 offset1:44
	s_waitcnt vmcnt(5)
	v_add_f32_e32 v58, v210, v58
	v_add_f32_e32 v59, v210, v59
	v_mfma_f32_16x16x32_bf16 v[70:73], v[138:141], v[46:49], v[74:77]
	v_add_f32_e32 v66, v210, v60
	v_add_f32_e32 v67, v210, v61
	s_nop 0
	v_add_f32_e32 v62, v210, v62
	v_mfma_f32_16x16x32_bf16 v[46:49], v[86:89], v[46:49], v[54:57]
	v_add_f32_e32 v63, v210, v63
	v_cvt_pk_f16_f32 v74, v58, v59
	v_cvt_pk_f16_f32 v75, v66, v67
	s_waitcnt vmcnt(4)
	v_mfma_f32_16x16x32_bf16 v[54:57], v[98:101], v[42:45], 0
	v_cvt_pk_f16_f32 v62, v62, v63
	v_add_f32_e32 v63, v210, v64
	v_add_f32_e32 v64, v210, v65
	s_waitcnt vmcnt(3)
	v_mfma_f32_16x16x32_bf16 v[54:57], v[118:121], v[30:33], v[54:57]
	v_cvt_pk_f16_f32 v63, v63, v64
	v_add_u32_e32 v76, 0x4000, v207
	ds_write2_b64 v76, v[74:75], v[62:63] offset0:64 offset1:68
	v_mfma_f32_16x16x32_bf16 v[58:61], v[110:113], v[42:45], 0
	v_add_f32_e32 v62, v210, v70
	v_add_f32_e32 v63, v210, v71
	v_cvt_pk_f16_f32 v70, v62, v63
	v_mfma_f32_16x16x32_bf16 v[66:69], v[106:109], v[42:45], 0
	v_add_f32_e32 v62, v210, v72
	v_add_f32_e32 v63, v210, v73
	v_cvt_pk_f16_f32 v71, v62, v63
	v_mfma_f32_16x16x32_bf16 v[42:45], v[102:105], v[42:45], 0
	v_add_f32_e32 v46, v210, v46
	v_add_f32_e32 v47, v210, v47
	s_waitcnt vmcnt(2)
	v_mfma_f32_16x16x32_bf16 v[54:57], v[134:137], v[26:29], v[54:57]
	v_mfma_f32_16x16x32_bf16 v[58:61], v[122:125], v[30:33], v[58:61]
	v_mfma_f32_16x16x32_bf16 v[62:65], v[126:129], v[30:33], v[66:69]
	v_mfma_f32_16x16x32_bf16 v[30:33], v[94:97], v[30:33], v[42:45]
	s_nop 1
	v_cvt_pk_f16_f32 v66, v46, v47
	v_add_f32_e32 v46, v210, v48
	v_add_f32_e32 v47, v210, v49
	v_cvt_pk_f16_f32 v67, v46, v47
	s_waitcnt vmcnt(1)
	v_mfma_f32_16x16x32_bf16 v[46:49], v[146:149], v[14:17], v[54:57]
	ds_write2_b64 v76, v[70:71], v[66:67] offset0:72 offset1:76
	v_mfma_f32_16x16x32_bf16 v[54:57], v[130:133], v[26:29], v[58:61]
	v_mfma_f32_16x16x32_bf16 v[42:45], v[114:117], v[26:29], v[62:65]
	s_waitcnt vmcnt(0)
	s_nop 3
	v_add_f32_e32 v46, v209, v46
	v_add_f32_e32 v47, v209, v47
	v_cvt_pk_f16_f32 v58, v46, v47
	v_mfma_f32_16x16x32_bf16 v[26:29], v[90:93], v[26:29], v[30:33]
	v_add_f32_e32 v59, v209, v48
	v_add_f32_e32 v60, v209, v49
	v_cvt_pk_f16_f32 v59, v59, v60
	v_mfma_f32_16x16x32_bf16 v[46:49], v[142:145], v[14:17], v[54:57]
	v_mfma_f32_16x16x32_bf16 v[42:45], v[138:141], v[14:17], v[42:45]
	v_mfma_f32_16x16x32_bf16 v[14:17], v[86:89], v[14:17], v[26:29]
	s_nop 5
	v_add_f32_e32 v46, v209, v46
	v_add_f32_e32 v47, v209, v47
	v_cvt_pk_f16_f32 v46, v46, v47
	v_add_f32_e32 v47, v209, v48
	v_add_f32_e32 v48, v209, v49
	v_add_f32_e32 v14, v209, v14
	v_add_f32_e32 v15, v209, v15
	v_add_f32_e32 v42, v209, v42
	v_add_f32_e32 v43, v209, v43
	v_add_f32_e32 v30, v209, v44
	v_add_f32_e32 v31, v209, v45
	v_cvt_pk_f16_f32 v14, v14, v15
	v_add_f32_e32 v15, v209, v16
	v_add_f32_e32 v16, v209, v17
	v_cvt_pk_f16_f32 v47, v47, v48
	v_add_u32_e32 v48, 0x6000, v207
	v_cvt_pk_f16_f32 v42, v42, v43
	v_cvt_pk_f16_f32 v43, v30, v31
	v_cvt_pk_f16_f32 v15, v15, v16
	ds_write2_b64 v48, v[58:59], v[46:47] offset0:96 offset1:100
	ds_write2_b64 v48, v[42:43], v[14:15] offset0:104 offset1:108
	s_waitcnt lgkmcnt(0)
	s_barrier
	global_load_dwordx4 v[62:65], v[184:185], off offset:3072
	global_load_dwordx4 v[58:61], v[182:183], off offset:3072
	global_load_dwordx4 v[54:57], v[180:181], off offset:3072
	global_load_dwordx4 v[46:49], v[178:179], off offset:3072
	global_load_dwordx4 v[42:45], v[176:177], off offset:3072
	global_load_dwordx4 v[30:33], v[174:175], off offset:3072
	global_load_dwordx4 v[26:29], v[172:173], off offset:3072
	global_load_dwordx4 v[14:17], v[170:171], off offset:3072
	ds_read_b128 v[66:69], v208
	v_lshlrev_b32_e32 v70, 16, v50
	v_and_b32_e32 v71, 0xffff0000, v50
	s_waitcnt vmcnt(7)
	v_lshlrev_b32_e32 v72, 16, v62
	v_and_b32_e32 v73, 0xffff0000, v62
	s_waitcnt lgkmcnt(0)
	v_cvt_f32_f16_e32 v74, v66
	v_cvt_f32_f16_sdwa v75, v66 dst_sel:DWORD dst_unused:UNUSED_PAD src0_sel:WORD_1
	v_cvt_f32_f16_e32 v66, v67
	v_cvt_f32_f16_sdwa v67, v67 dst_sel:DWORD dst_unused:UNUSED_PAD src0_sel:WORD_1
	v_lshlrev_b32_e32 v62, 16, v63
	v_pk_mul_f32 v[70:71], v[70:71], v[74:75]
	v_and_b32_e32 v63, 0xffff0000, v63
	v_pk_mul_f32 v[70:71], v[70:71], v[72:73]
	s_add_i32 s16, s16, s5
	v_cvt_pk_bf16_f32 v50, v70, v71
	v_lshlrev_b32_e32 v70, 16, v51
	v_and_b32_e32 v71, 0xffff0000, v51
	v_pk_mul_f32 v[66:67], v[70:71], v[66:67]
	v_cvt_f32_f16_e32 v70, v68
	v_cvt_f32_f16_sdwa v71, v68 dst_sel:DWORD dst_unused:UNUSED_PAD src0_sel:WORD_1
	v_pk_mul_f32 v[62:63], v[66:67], v[62:63]
	v_lshlrev_b32_e32 v66, 16, v64
	v_cvt_pk_bf16_f32 v51, v62, v63
	v_lshlrev_b32_e32 v62, 16, v52
	v_and_b32_e32 v63, 0xffff0000, v52
	v_and_b32_e32 v67, 0xffff0000, v64
	v_pk_mul_f32 v[62:63], v[62:63], v[70:71]
	v_lshlrev_b32_e32 v64, 16, v65
	v_pk_mul_f32 v[62:63], v[62:63], v[66:67]
	v_cvt_f32_f16_e32 v66, v69
	v_cvt_f32_f16_sdwa v67, v69 dst_sel:DWORD dst_unused:UNUSED_PAD src0_sel:WORD_1
	v_cvt_pk_bf16_f32 v52, v62, v63
	v_lshlrev_b32_e32 v62, 16, v53
	v_and_b32_e32 v63, 0xffff0000, v53
	v_and_b32_e32 v65, 0xffff0000, v65
	v_pk_mul_f32 v[62:63], v[62:63], v[66:67]
	v_add_u32_e32 v0, s17, v0
	v_pk_mul_f32 v[62:63], v[62:63], v[64:65]
	s_waitcnt vmcnt(6)
	v_lshlrev_b32_e32 v64, 16, v58
	v_cvt_pk_bf16_f32 v53, v62, v63
	global_store_dwordx4 v[184:185], v[50:53], off offset:512
	ds_read_b128 v[50:53], v208 offset:8448
	v_lshlrev_b32_e32 v62, 16, v38
	v_and_b32_e32 v63, 0xffff0000, v38
	v_and_b32_e32 v65, 0xffff0000, v58
	v_lshlrev_b32_e32 v58, 16, v59
	s_waitcnt lgkmcnt(0)
	v_cvt_f32_f16_e32 v66, v50
	v_cvt_f32_f16_sdwa v67, v50 dst_sel:DWORD dst_unused:UNUSED_PAD src0_sel:WORD_1
	v_cvt_f32_f16_e32 v50, v51
	v_cvt_f32_f16_sdwa v51, v51 dst_sel:DWORD dst_unused:UNUSED_PAD src0_sel:WORD_1
	v_and_b32_e32 v59, 0xffff0000, v59
	v_pk_mul_f32 v[62:63], v[62:63], v[66:67]
	s_cmpk_lt_i32 s16, 0x180
	v_pk_mul_f32 v[62:63], v[62:63], v[64:65]
	s_nop 0
	v_cvt_pk_bf16_f32 v38, v62, v63
	v_lshlrev_b32_e32 v62, 16, v39
	v_and_b32_e32 v63, 0xffff0000, v39
	v_pk_mul_f32 v[50:51], v[62:63], v[50:51]
	v_cvt_f32_f16_e32 v62, v52
	v_cvt_f32_f16_sdwa v63, v52 dst_sel:DWORD dst_unused:UNUSED_PAD src0_sel:WORD_1
	v_pk_mul_f32 v[50:51], v[50:51], v[58:59]
	v_cvt_f32_f16_e32 v52, v53
	v_cvt_pk_bf16_f32 v39, v50, v51
	v_lshlrev_b32_e32 v50, 16, v40
	v_and_b32_e32 v51, 0xffff0000, v40
	v_cvt_f32_f16_sdwa v53, v53 dst_sel:DWORD dst_unused:UNUSED_PAD src0_sel:WORD_1
	v_lshlrev_b32_e32 v58, 16, v60
	v_and_b32_e32 v59, 0xffff0000, v60
	v_pk_mul_f32 v[50:51], v[50:51], v[62:63]
	s_nop 0
	v_pk_mul_f32 v[50:51], v[50:51], v[58:59]
	v_lshlrev_b32_e32 v58, 16, v61
	v_cvt_pk_bf16_f32 v40, v50, v51
	v_lshlrev_b32_e32 v50, 16, v41
	v_and_b32_e32 v51, 0xffff0000, v41
	v_and_b32_e32 v59, 0xffff0000, v61
	v_pk_mul_f32 v[50:51], v[50:51], v[52:53]
	s_waitcnt vmcnt(6)
	v_lshlrev_b32_e32 v52, 16, v54
	v_pk_mul_f32 v[50:51], v[50:51], v[58:59]
	v_and_b32_e32 v53, 0xffff0000, v54
	v_cvt_pk_bf16_f32 v41, v50, v51
	global_store_dwordx4 v[182:183], v[38:41], off offset:512
	ds_read_b128 v[38:41], v208 offset:16896
	v_lshlrev_b32_e32 v50, 16, v34
	v_and_b32_e32 v51, 0xffff0000, v34
	s_waitcnt lgkmcnt(0)
	v_cvt_f32_f16_e32 v58, v38
	v_cvt_f32_f16_sdwa v59, v38 dst_sel:DWORD dst_unused:UNUSED_PAD src0_sel:WORD_1
	v_cvt_f32_f16_e32 v38, v39
	v_cvt_f32_f16_sdwa v39, v39 dst_sel:DWORD dst_unused:UNUSED_PAD src0_sel:WORD_1
	v_pk_mul_f32 v[50:51], v[50:51], v[58:59]
	s_nop 0
	v_pk_mul_f32 v[50:51], v[50:51], v[52:53]
	v_lshlrev_b32_e32 v52, 16, v55
	v_cvt_pk_bf16_f32 v34, v50, v51
	v_lshlrev_b32_e32 v50, 16, v35
	v_and_b32_e32 v51, 0xffff0000, v35
	v_and_b32_e32 v53, 0xffff0000, v55
	v_pk_mul_f32 v[38:39], v[50:51], v[38:39]
	v_lshlrev_b32_e32 v50, 16, v56
	v_pk_mul_f32 v[38:39], v[38:39], v[52:53]
	v_cvt_f32_f16_e32 v52, v40
	v_cvt_f32_f16_sdwa v53, v40 dst_sel:DWORD dst_unused:UNUSED_PAD src0_sel:WORD_1
	v_cvt_pk_bf16_f32 v35, v38, v39
	v_lshlrev_b32_e32 v38, 16, v36
	v_and_b32_e32 v39, 0xffff0000, v36
	v_cvt_f32_f16_e32 v40, v41
	v_cvt_f32_f16_sdwa v41, v41 dst_sel:DWORD dst_unused:UNUSED_PAD src0_sel:WORD_1
	v_and_b32_e32 v51, 0xffff0000, v56
	v_pk_mul_f32 v[38:39], v[38:39], v[52:53]
	s_nop 0
	v_pk_mul_f32 v[38:39], v[38:39], v[50:51]
	v_lshlrev_b32_e32 v50, 16, v57
	v_cvt_pk_bf16_f32 v36, v38, v39
	v_lshlrev_b32_e32 v38, 16, v37
	v_and_b32_e32 v39, 0xffff0000, v37
	v_and_b32_e32 v51, 0xffff0000, v57
	v_pk_mul_f32 v[38:39], v[38:39], v[40:41]
	s_waitcnt vmcnt(6)
	v_lshlrev_b32_e32 v40, 16, v46
	v_pk_mul_f32 v[38:39], v[38:39], v[50:51]
	v_and_b32_e32 v41, 0xffff0000, v46
	v_cvt_pk_bf16_f32 v37, v38, v39
	global_store_dwordx4 v[180:181], v[34:37], off offset:512
	ds_read_b128 v[34:37], v208 offset:25344
	v_lshlrev_b32_e32 v38, 16, v22
	v_and_b32_e32 v39, 0xffff0000, v22
	s_waitcnt lgkmcnt(0)
	v_cvt_f32_f16_e32 v50, v34
	v_cvt_f32_f16_sdwa v51, v34 dst_sel:DWORD dst_unused:UNUSED_PAD src0_sel:WORD_1
	v_cvt_f32_f16_e32 v34, v35
	v_cvt_f32_f16_sdwa v35, v35 dst_sel:DWORD dst_unused:UNUSED_PAD src0_sel:WORD_1
	v_pk_mul_f32 v[38:39], v[38:39], v[50:51]
	s_nop 0
	v_pk_mul_f32 v[38:39], v[38:39], v[40:41]
	v_lshlrev_b32_e32 v40, 16, v47
	v_cvt_pk_bf16_f32 v22, v38, v39
	v_lshlrev_b32_e32 v38, 16, v23
	v_and_b32_e32 v39, 0xffff0000, v23
	v_and_b32_e32 v41, 0xffff0000, v47
	v_pk_mul_f32 v[34:35], v[38:39], v[34:35]
	v_lshlrev_b32_e32 v38, 16, v48
	v_pk_mul_f32 v[34:35], v[34:35], v[40:41]
	v_cvt_f32_f16_e32 v40, v36
	v_cvt_f32_f16_sdwa v41, v36 dst_sel:DWORD dst_unused:UNUSED_PAD src0_sel:WORD_1
	v_cvt_pk_bf16_f32 v23, v34, v35
	v_lshlrev_b32_e32 v34, 16, v24
	v_and_b32_e32 v35, 0xffff0000, v24
	v_cvt_f32_f16_e32 v36, v37
	v_cvt_f32_f16_sdwa v37, v37 dst_sel:DWORD dst_unused:UNUSED_PAD src0_sel:WORD_1
	v_and_b32_e32 v39, 0xffff0000, v48
	v_pk_mul_f32 v[34:35], v[34:35], v[40:41]
	s_nop 0
	v_pk_mul_f32 v[34:35], v[34:35], v[38:39]
	v_lshlrev_b32_e32 v38, 16, v49
	v_cvt_pk_bf16_f32 v24, v34, v35
	v_lshlrev_b32_e32 v34, 16, v25
	v_and_b32_e32 v35, 0xffff0000, v25
	v_and_b32_e32 v39, 0xffff0000, v49
	v_pk_mul_f32 v[34:35], v[34:35], v[36:37]
	s_waitcnt vmcnt(6)
	v_lshlrev_b32_e32 v36, 16, v42
	v_pk_mul_f32 v[34:35], v[34:35], v[38:39]
	v_and_b32_e32 v37, 0xffff0000, v42
	v_cvt_pk_bf16_f32 v25, v34, v35
	global_store_dwordx4 v[178:179], v[22:25], off offset:512
	ds_read_b128 v[22:25], v208 offset:33792
	v_lshlrev_b32_e32 v34, 16, v18
	v_and_b32_e32 v35, 0xffff0000, v18
	s_waitcnt lgkmcnt(0)
	v_cvt_f32_f16_e32 v38, v22
	v_cvt_f32_f16_sdwa v39, v22 dst_sel:DWORD dst_unused:UNUSED_PAD src0_sel:WORD_1
	v_cvt_f32_f16_e32 v22, v23
	v_cvt_f32_f16_sdwa v23, v23 dst_sel:DWORD dst_unused:UNUSED_PAD src0_sel:WORD_1
	v_pk_mul_f32 v[34:35], v[34:35], v[38:39]
	s_nop 0
	v_pk_mul_f32 v[34:35], v[34:35], v[36:37]
	v_lshlrev_b32_e32 v36, 16, v43
	v_cvt_pk_bf16_f32 v18, v34, v35
	v_lshlrev_b32_e32 v34, 16, v19
	v_and_b32_e32 v35, 0xffff0000, v19
	v_and_b32_e32 v37, 0xffff0000, v43
	v_pk_mul_f32 v[22:23], v[34:35], v[22:23]
	v_lshlrev_b32_e32 v34, 16, v44
	v_pk_mul_f32 v[22:23], v[22:23], v[36:37]
	v_cvt_f32_f16_e32 v36, v24
	v_cvt_f32_f16_sdwa v37, v24 dst_sel:DWORD dst_unused:UNUSED_PAD src0_sel:WORD_1
	v_cvt_pk_bf16_f32 v19, v22, v23
	v_lshlrev_b32_e32 v22, 16, v20
	v_and_b32_e32 v23, 0xffff0000, v20
	v_cvt_f32_f16_e32 v24, v25
	v_cvt_f32_f16_sdwa v25, v25 dst_sel:DWORD dst_unused:UNUSED_PAD src0_sel:WORD_1
	v_and_b32_e32 v35, 0xffff0000, v44
	v_pk_mul_f32 v[22:23], v[22:23], v[36:37]
	s_nop 0
	v_pk_mul_f32 v[22:23], v[22:23], v[34:35]
	v_lshlrev_b32_e32 v34, 16, v45
	v_cvt_pk_bf16_f32 v20, v22, v23
	v_lshlrev_b32_e32 v22, 16, v21
	v_and_b32_e32 v23, 0xffff0000, v21
	v_and_b32_e32 v35, 0xffff0000, v45
	v_pk_mul_f32 v[22:23], v[22:23], v[24:25]
	s_waitcnt vmcnt(6)
	v_lshlrev_b32_e32 v24, 16, v30
	v_pk_mul_f32 v[22:23], v[22:23], v[34:35]
	v_and_b32_e32 v25, 0xffff0000, v30
	v_cvt_pk_bf16_f32 v21, v22, v23
	global_store_dwordx4 v[176:177], v[18:21], off offset:512
	ds_read_b128 v[18:21], v208 offset:42240
	v_lshlrev_b32_e32 v22, 16, v10
	v_and_b32_e32 v23, 0xffff0000, v10
	s_waitcnt lgkmcnt(0)
	v_cvt_f32_f16_e32 v34, v18
	v_cvt_f32_f16_sdwa v35, v18 dst_sel:DWORD dst_unused:UNUSED_PAD src0_sel:WORD_1
	v_cvt_f32_f16_e32 v18, v19
	v_cvt_f32_f16_sdwa v19, v19 dst_sel:DWORD dst_unused:UNUSED_PAD src0_sel:WORD_1
	v_pk_mul_f32 v[22:23], v[22:23], v[34:35]
	s_nop 0
	v_pk_mul_f32 v[22:23], v[22:23], v[24:25]
	v_lshlrev_b32_e32 v24, 16, v31
	v_cvt_pk_bf16_f32 v10, v22, v23
	v_lshlrev_b32_e32 v22, 16, v11
	v_and_b32_e32 v23, 0xffff0000, v11
	v_and_b32_e32 v25, 0xffff0000, v31
	v_pk_mul_f32 v[18:19], v[22:23], v[18:19]
	v_lshlrev_b32_e32 v22, 16, v32
	v_pk_mul_f32 v[18:19], v[18:19], v[24:25]
	v_cvt_f32_f16_e32 v24, v20
	v_cvt_f32_f16_sdwa v25, v20 dst_sel:DWORD dst_unused:UNUSED_PAD src0_sel:WORD_1
	v_cvt_pk_bf16_f32 v11, v18, v19
	v_lshlrev_b32_e32 v18, 16, v12
	v_and_b32_e32 v19, 0xffff0000, v12
	v_cvt_f32_f16_e32 v20, v21
	v_cvt_f32_f16_sdwa v21, v21 dst_sel:DWORD dst_unused:UNUSED_PAD src0_sel:WORD_1
	v_and_b32_e32 v23, 0xffff0000, v32
	v_pk_mul_f32 v[18:19], v[18:19], v[24:25]
	s_nop 0
	v_pk_mul_f32 v[18:19], v[18:19], v[22:23]
	v_lshlrev_b32_e32 v22, 16, v33
	v_cvt_pk_bf16_f32 v12, v18, v19
	v_lshlrev_b32_e32 v18, 16, v13
	v_and_b32_e32 v19, 0xffff0000, v13
	v_and_b32_e32 v23, 0xffff0000, v33
	v_pk_mul_f32 v[18:19], v[18:19], v[20:21]
	s_waitcnt vmcnt(6)
	v_lshlrev_b32_e32 v20, 16, v26
	v_pk_mul_f32 v[18:19], v[18:19], v[22:23]
	v_and_b32_e32 v21, 0xffff0000, v26
	v_cvt_pk_bf16_f32 v13, v18, v19
	global_store_dwordx4 v[174:175], v[10:13], off offset:512
	ds_read_b128 v[10:13], v208 offset:50688
	v_lshlrev_b32_e32 v18, 16, v6
	v_and_b32_e32 v19, 0xffff0000, v6
	s_waitcnt lgkmcnt(0)
	v_cvt_f32_f16_e32 v22, v10
	v_cvt_f32_f16_sdwa v23, v10 dst_sel:DWORD dst_unused:UNUSED_PAD src0_sel:WORD_1
	v_cvt_f32_f16_e32 v10, v11
	v_cvt_f32_f16_sdwa v11, v11 dst_sel:DWORD dst_unused:UNUSED_PAD src0_sel:WORD_1
	v_pk_mul_f32 v[18:19], v[18:19], v[22:23]
	s_nop 0
	v_pk_mul_f32 v[18:19], v[18:19], v[20:21]
	v_lshlrev_b32_e32 v20, 16, v27
	v_cvt_pk_bf16_f32 v6, v18, v19
	v_lshlrev_b32_e32 v18, 16, v7
	v_and_b32_e32 v19, 0xffff0000, v7
	v_and_b32_e32 v21, 0xffff0000, v27
	v_pk_mul_f32 v[10:11], v[18:19], v[10:11]
	v_lshlrev_b32_e32 v18, 16, v28
	v_pk_mul_f32 v[10:11], v[10:11], v[20:21]
	v_cvt_f32_f16_e32 v20, v12
	v_cvt_f32_f16_sdwa v21, v12 dst_sel:DWORD dst_unused:UNUSED_PAD src0_sel:WORD_1
	v_cvt_pk_bf16_f32 v7, v10, v11
	v_lshlrev_b32_e32 v10, 16, v8
	v_and_b32_e32 v11, 0xffff0000, v8
	v_cvt_f32_f16_e32 v12, v13
	v_cvt_f32_f16_sdwa v13, v13 dst_sel:DWORD dst_unused:UNUSED_PAD src0_sel:WORD_1
	v_and_b32_e32 v19, 0xffff0000, v28
	v_pk_mul_f32 v[10:11], v[10:11], v[20:21]
	s_nop 0
	v_pk_mul_f32 v[10:11], v[10:11], v[18:19]
	v_lshlrev_b32_e32 v18, 16, v29
	v_cvt_pk_bf16_f32 v8, v10, v11
	v_lshlrev_b32_e32 v10, 16, v9
	v_and_b32_e32 v11, 0xffff0000, v9
	v_and_b32_e32 v19, 0xffff0000, v29
	v_pk_mul_f32 v[10:11], v[10:11], v[12:13]
	s_waitcnt vmcnt(6)
	v_lshlrev_b32_e32 v12, 16, v14
	v_pk_mul_f32 v[10:11], v[10:11], v[18:19]
	v_and_b32_e32 v13, 0xffff0000, v14
	v_cvt_pk_bf16_f32 v9, v10, v11
	global_store_dwordx4 v[172:173], v[6:9], off offset:512
	ds_read_b128 v[6:9], v208 offset:59136
	v_lshlrev_b32_e32 v10, 16, v2
	v_and_b32_e32 v11, 0xffff0000, v2
	s_waitcnt lgkmcnt(0)
	v_cvt_f32_f16_e32 v18, v6
	v_cvt_f32_f16_sdwa v19, v6 dst_sel:DWORD dst_unused:UNUSED_PAD src0_sel:WORD_1
	v_cvt_f32_f16_e32 v6, v7
	v_cvt_f32_f16_sdwa v7, v7 dst_sel:DWORD dst_unused:UNUSED_PAD src0_sel:WORD_1
	v_pk_mul_f32 v[10:11], v[10:11], v[18:19]
	s_nop 0
	v_pk_mul_f32 v[10:11], v[10:11], v[12:13]
	v_lshlrev_b32_e32 v12, 16, v15
	v_cvt_pk_bf16_f32 v2, v10, v11
	v_lshlrev_b32_e32 v10, 16, v3
	v_and_b32_e32 v11, 0xffff0000, v3
	v_and_b32_e32 v13, 0xffff0000, v15
	v_pk_mul_f32 v[6:7], v[10:11], v[6:7]
	v_lshlrev_b32_e32 v10, 16, v16
	v_pk_mul_f32 v[6:7], v[6:7], v[12:13]
	v_cvt_f32_f16_e32 v12, v8
	v_cvt_f32_f16_sdwa v13, v8 dst_sel:DWORD dst_unused:UNUSED_PAD src0_sel:WORD_1
	v_cvt_pk_bf16_f32 v3, v6, v7
	v_lshlrev_b32_e32 v6, 16, v4
	v_and_b32_e32 v7, 0xffff0000, v4
	v_cvt_f32_f16_e32 v8, v9
	v_cvt_f32_f16_sdwa v9, v9 dst_sel:DWORD dst_unused:UNUSED_PAD src0_sel:WORD_1
	v_and_b32_e32 v11, 0xffff0000, v16
	v_pk_mul_f32 v[6:7], v[6:7], v[12:13]
	s_nop 0
	v_pk_mul_f32 v[6:7], v[6:7], v[10:11]
	v_lshlrev_b32_e32 v10, 16, v17
	v_cvt_pk_bf16_f32 v4, v6, v7
	v_lshlrev_b32_e32 v6, 16, v5
	v_and_b32_e32 v7, 0xffff0000, v5
	v_and_b32_e32 v11, 0xffff0000, v17
	v_pk_mul_f32 v[6:7], v[6:7], v[8:9]
	s_nop 0
	v_pk_mul_f32 v[6:7], v[6:7], v[10:11]
	s_nop 0
	v_cvt_pk_bf16_f32 v5, v6, v7
	global_store_dwordx4 v[170:171], v[2:5], off offset:512
	s_barrier
	s_cbranch_scc1 .LBB0_684
	s_mov_b64 s[38:39], s[58:59]
	s_andn2_b64 vcc, exec, s[38:39]
	s_mov_b32 s0, s24
	s_cbranch_vccnz .LBB0_688
